# speedup vs baseline: 1.0532x; 1.0151x over previous
.LBB0_31:
	s_waitcnt vmcnt(0)
	v_mov_b32_e32 v2, v195
	s_load_dwordx8 s[64:71], s[84:85], 0xc8
	s_bfe_u32 s35, s55, 0x50003
	v_readfirstlane_b32 s49, v2
	s_xor_b32 s37, s35, 63
	s_ashr_i32 s3, s49, 1
	s_ashr_i32 s46, s55, 8
	s_lshl_b32 s2, s37, 8
	s_and_b32 s53, s3, 0xffffffe0
	s_and_b32 s48, s54, 7
	s_waitcnt lgkmcnt(0)
	s_mov_b64 s[60:61], s[64:65]
	s_add_i32 s53, s53, s2
	s_ashr_i32 s47, s46, 31
	s_lshl_b32 s52, s48, 9
	s_lshr_b32 s56, s55, 3
	s_and_b32 s42, s55, 7
	s_mov_b64 s[62:63], s[66:67]
	s_mov_b64 s[64:65], s[68:69]
	s_mov_b64 s[66:67], s[70:71]
	s_lshl_b64 s[2:3], s[46:47], 14
	s_ashr_i32 s20, s53, 31
	v_and_b32_e32 v23, 31, v2
	s_mov_b64 s[30:31], s[66:67]
	s_add_u32 s36, s2, s53
	v_or_b32_e32 v3, s36, v23
	v_mov_b64_e32 v[0:1], s[30:31]
	s_addc_u32 s20, s3, s20
	v_mad_u64_u32 v[0:1], s[30:31], v3, s39, v[0:1]
	s_mul_i32 s36, s42, 0xc0
	v_mad_i32_i24 v1, s20, v248, v1
	s_lshl_b32 s20, s36, 1
	s_lshl_b32 s62, s37, 2
	v_bfe_u32 v36, v2, 5, 1
	s_mov_b64 s[40:41], s[66:67]
	v_lshl_add_u64 v[0:1], v[0:1], 0, s[20:21]
	s_mov_b64 s[30:31], 0xd808000
	s_add_i32 s59, s62, 4
	s_lshl_b64 s[44:45], s[46:47], 26
	v_lshl_add_u64 v[186:187], v[0:1], 0, s[30:31]
	v_lshlrev_b32_e32 v184, 4, v36
	s_add_u32 s30, s40, s44
	s_mov_b64 s[26:27], s[66:67]
	s_mov_b64 s[50:51], s[66:67]
	v_lshl_add_u64 v[0:1], v[186:187], 0, v[184:185]
	s_addc_u32 s31, s41, s45
	s_lshl_b32 s37, s42, 8
	s_lshl_b32 s43, s42, 9
	v_and_b32_e32 v3, 15, v2
	global_load_dwordx4 v[96:99], v[0:1], off
	global_load_dwordx4 v[100:103], v[0:1], off offset:32
	global_load_dwordx4 v[104:107], v[0:1], off offset:64
	global_load_dwordx4 v[108:111], v[0:1], off offset:96
	global_load_dwordx4 v[112:115], v[0:1], off offset:128
	global_load_dwordx4 v[116:119], v[0:1], off offset:160
	global_load_dwordx4 v[120:123], v[0:1], off offset:192
	global_load_dwordx4 v[124:127], v[0:1], off offset:224
	global_load_dwordx4 v[128:131], v[0:1], off offset:256
	global_load_dwordx4 v[132:135], v[0:1], off offset:288
	global_load_dwordx4 v[136:139], v[0:1], off offset:320
	global_load_dwordx4 v[140:143], v[0:1], off offset:352
	s_add_u32 s80, s30, s43
	v_ashrrev_i32_e32 v1, 4, v2
	v_lshlrev_b32_e32 v0, 3, v3
	s_addc_u32 s81, s31, 0
	s_lshl_b32 s57, s46, 3
	v_lshl_or_b32 v0, v1, 11, v0
	v_mul_lo_u32 v1, v1, s29
	s_lshl_b64 s[30:31], s[46:47], 21
	s_or_b32 s46, s57, s42
	v_lshl_add_u32 v38, v3, 4, v1
	v_and_b32_e32 v1, 7, v2
	s_ashr_i32 s47, s46, 31
	v_ashrrev_i32_e32 v39, 3, v2
	v_lshlrev_b32_e32 v2, 3, v1
	v_lshlrev_b32_e32 v22, 4, v1
	v_ashrrev_i32_e32 v1, 31, v0
	s_lshl_b64 s[46:47], s[46:47], 22
	v_lshlrev_b64 v[0:1], 1, v[0:1]
	s_add_u32 s94, s50, s46
	v_lshl_add_u64 v[26:27], s[80:81], 0, v[0:1]
	s_mov_b32 s28, 0x13808000
	s_addc_u32 s95, s51, s47
	v_lshl_or_b32 v10, v39, 6, v2
	v_lshl_or_b32 v14, v39, 14, v2
	v_add_co_u32_e32 v2, vcc, s28, v26
	s_mov_b32 s28, 0x13828000
	s_nop 0
	v_addc_co_u32_e32 v3, vcc, 0, v27, vcc
	s_add_u32 s26, s26, s30
	v_add_co_u32_e32 v6, vcc, s28, v26
	v_ashrrev_i32_e32 v11, 31, v10
	s_addc_u32 s27, s27, s31
	v_ashrrev_i32_e32 v15, 31, v14
	v_addc_co_u32_e32 v7, vcc, 0, v27, vcc
	v_lshl_add_u64 v[28:29], v[10:11], 1, s[26:27]
	s_mov_b32 s26, 0xd408000
	v_lshlrev_b64 v[30:31], 1, v[14:15]
	v_add_co_u32_e32 v10, vcc, s26, v28
	v_lshl_add_u64 v[18:19], s[94:95], 0, v[30:31]
	s_mov_b64 s[26:27], 0x5808000
	v_addc_co_u32_e32 v11, vcc, 0, v29, vcc
	v_lshl_add_u64 v[32:33], v[18:19], 0, s[26:27]
	s_mov_b32 s26, 0x5808000
	v_add_co_u32_e32 v14, vcc, s26, v18
	global_load_dwordx4 v[2:5], v[2:3], off
	s_nop 0
	v_addc_co_u32_e32 v15, vcc, 0, v19, vcc
	s_mov_b32 s26, 0x5a08000
	global_load_dwordx4 v[6:9], v[6:7], off
	v_add_co_u32_e32 v34, vcc, s26, v18
	global_load_dwordx4 v[10:13], v[10:11], off
	s_nop 0
	v_addc_co_u32_e32 v35, vcc, 0, v19, vcc
	global_load_dwordx4 v[14:17], v[14:15], off
	s_movk_i32 s68, 0x88
	global_load_dwordx4 v[18:21], v[34:35], off
	v_mad_u64_u32 v[24:25], s[96:97], v39, s68, v[22:23]
	v_add_u32_e32 v250, 0, v38
	s_movk_i32 s26, 0x108
	s_waitcnt lgkmcnt(0)
	s_barrier
	s_waitcnt vmcnt(0)
	ds_write_b128 v250, v[2:5]
	ds_write_b128 v250, v[6:9] offset:12800
	v_mad_u64_u32 v[2:3], s[26:27], v39, s26, v[24:25]
	v_add_u32_e32 v252, 0, v24
	s_mov_b32 s26, 0x13848000
	v_add_u32_e32 v251, 0, v2
	v_add_u32_e32 v253, 0xc800, v252
	v_add_u32_e32 v254, 0xea00, v252
	v_add_co_u32_e32 v2, vcc, s26, v26
	ds_write_b128 v251, v[10:13] offset:256
	ds_write2_b64 v253, v[14:15], v[16:17] offset1:1
	ds_write2_b64 v254, v[18:19], v[20:21] offset1:1
	v_addc_co_u32_e32 v3, vcc, 0, v27, vcc
	s_mov_b32 s26, 0x13868000
	global_load_dwordx4 v[144:147], v[2:3], off
	v_add_co_u32_e32 v2, vcc, s26, v26
	s_mov_b32 s26, 0xd40a000
	s_nop 0
	v_addc_co_u32_e32 v3, vcc, 0, v27, vcc
	global_load_dwordx4 v[148:151], v[2:3], off
	v_add_co_u32_e32 v2, vcc, s26, v28
	s_or_b32 s48, s57, s48
	s_nop 0
	v_addc_co_u32_e32 v3, vcc, 0, v29, vcc
	global_load_dwordx4 v[152:155], v[2:3], off
	global_load_dwordx4 v[156:159], v[32:33], off offset:128
	global_load_dwordx4 v[160:163], v[34:35], off offset:128
	s_ashr_i32 s26, s49, 7
	s_ashr_i32 s49, s48, 31
	s_lshl_b64 s[48:49], s[48:49], 22
	s_add_u32 s50, s50, s48
	v_mad_u32_u24 v213, v23, s29, 0
	s_movk_i32 s27, 0xfef8
	s_addc_u32 s51, s51, s49
	s_or_b32 s57, s44, s52
	v_mad_i32_i24 v18, v23, s27, v213
	v_readlane_b32 s27, v246, 47
	s_add_u32 s40, s40, s57
	v_mad_u64_u32 v[16:17], s[80:81], v39, s29, v[22:23]
	v_mov_b32_e32 v2, s27
	s_mov_b64 s[42:43], 0xd40e000
	s_addc_u32 s41, s41, s45
	v_lshlrev_b32_e32 v37, 3, v36
	v_readlane_b32 s96, v246, 55
	v_mad_u32_u24 v17, v23, s68, v2
	v_lshl_add_u64 v[188:189], v[28:29], 0, s[42:43]
	v_lshl_add_u64 v[2:3], s[50:51], 0, v[30:31]
; #define ATT_LOAD(kr, vr, t) do { const bf16_t* kp_ = KVb + (size_t)(t) * 64 * 2048 + kn_off; \
;         kr[0] = *(const u32x4*)kp_; kr[1] = *(const u32x4*)(kp_ + 32 * 2048); kr[2] = *(const u32x4*)(KPEb + (t) * 64 * 64 + kp_off); \
;         const bf16_t* vp_ = VTb + (t) * 64 + v_off; vr[0] = *(const u32x4*)vp_; vr[1] = *(const u32x4*)(vp_ + 64 * SEQ); } while (0)
; DI void attn_unit(const Params& P, LAS unsigned char* lds, int b, int h, int qb, bool dry) {
;     ...
;     f32x16 o[4];
; #pragma unroll
;     for (int d = 0; d < 4; ++d)
; #pragma unroll
;         for (int i = 0; i < 16; ++i) o[d][i] = 0.f;
;     float mrun = -INFINITY, lrun = 0.f;
;     const int nt = 4 * (qb + 1);
;     const bf16_t* KVb = KV + (size_t)b * SEQ * 2048 + h * 256; const bf16_t* KPEb = KPE + (size_t)b * SEQ * 64; const bf16_t* VTb = VT + (size_t)(b * 8 + h) * 128 * SEQ;
;     ...
;     for (int kt = 0; kt < nt; kt += 2) {
;         const bool more2 = kt + 2 < nt;
;         if (more2) ATT_LOAD(kB, vB, kt + 2);
	s_mov_b64 s[42:43], 0x5a08180
	v_lshl_add_u64 v[0:1], s[40:41], 0, v[0:1]
	s_mov_b64 s[40:41], 0x138e8000
	v_mov_b32_e32 v14, v185
	v_mov_b32_e32 v15, v185
	v_readlane_b32 s97, v246, 56
	v_readlane_b32 s94, v246, 63
	v_or_b32_e32 v214, s53, v23
	v_lshlrev_b32_e32 v212, 2, v36
	v_lshl_add_u64 v[190:191], v[2:3], 0, s[42:43]
	v_lshl_add_u64 v[192:193], v[0:1], 0, s[40:41]
	s_add_i32 s40, s26, s62
	v_mov_b32_e32 v0, v185
	v_mov_b32_e32 v1, v185
	v_mov_b32_e32 v2, v185
	v_mov_b32_e32 v3, v185
	v_mov_b32_e32 v4, v185
	v_mov_b32_e32 v5, v185
	v_mov_b32_e32 v6, v185
	v_mov_b32_e32 v7, v185
	v_mov_b32_e32 v8, v185
	v_mov_b32_e32 v9, v185
	v_mov_b32_e32 v10, v185
	v_mov_b32_e32 v11, v185
	v_mov_b32_e32 v12, v185
	v_mov_b32_e32 v13, v185
	v_add_u32_e32 v216, v18, v37
	v_add_u32_e32 v217, 0, v16
	v_add_u32_e32 v218, v17, v37
	v_mov_b64_e32 v[30:31], v[14:15]
	v_mov_b64_e32 v[46:47], v[14:15]
	v_mov_b64_e32 v[62:63], v[14:15]
	s_mov_b32 s20, 2
	v_readlane_b32 s98, v246, 57
	v_readlane_b32 s95, v245, 0
	v_readlane_b32 s71, v246, 62
	v_readlane_b32 s69, v246, 61
	s_mov_b32 s81, 0x14000
	v_readlane_b32 s28, v246, 54
	s_mov_b32 s58, s45
	s_sub_i32 s27, 1, s40
	s_sub_i32 s62, 0, s62
	s_sub_i32 s63, 0, s40
	v_mov_b32_e32 v194, 0xff800000
	v_mov_b32_e32 v196, 0
	v_mov_b32_e32 v197, 0
	v_mov_b32_e32 v198, 0
	v_mov_b32_e32 v199, 0
	v_mov_b32_e32 v200, 0
	v_mov_b32_e32 v201, 0
	v_mov_b32_e32 v202, 0
	v_mov_b32_e32 v203, 0
	v_mov_b32_e32 v204, 0
	v_mov_b32_e32 v205, 0
	v_mov_b32_e32 v206, 0
	v_mov_b32_e32 v207, 0
	v_mov_b32_e32 v208, 0
	v_mov_b32_e32 v209, 0
	v_mov_b32_e32 v210, 0
	v_mov_b32_e32 v211, 0
	v_mov_b32_e32 v215, 0
	v_mov_b32_e32 v219, v212
	v_mov_b64_e32 v[28:29], v[12:13]
	v_mov_b64_e32 v[26:27], v[10:11]
	v_mov_b64_e32 v[24:25], v[8:9]
	v_mov_b64_e32 v[22:23], v[6:7]
	v_mov_b64_e32 v[20:21], v[4:5]
	v_mov_b64_e32 v[18:19], v[2:3]
	v_mov_b64_e32 v[16:17], v[0:1]
	v_mov_b64_e32 v[44:45], v[12:13]
	v_mov_b64_e32 v[42:43], v[10:11]
	v_mov_b64_e32 v[40:41], v[8:9]
	v_mov_b64_e32 v[38:39], v[6:7]
	v_mov_b64_e32 v[36:37], v[4:5]
	v_mov_b64_e32 v[34:35], v[2:3]
	v_mov_b64_e32 v[32:33], v[0:1]
	v_mov_b64_e32 v[60:61], v[12:13]
	v_mov_b64_e32 v[58:59], v[10:11]
	v_mov_b64_e32 v[56:57], v[8:9]
	v_mov_b64_e32 v[54:55], v[6:7]
	v_mov_b64_e32 v[52:53], v[4:5]
	v_mov_b64_e32 v[50:51], v[2:3]
	v_mov_b64_e32 v[48:49], v[0:1]
	s_mov_b64 s[96:97], 0x4000
	v_readlane_b32 s99, v246, 58
	v_add_co_u32_e32 v64, vcc, 0xfffa0000, v192
	s_nop 1
	v_addc_co_u32_e32 v65, vcc, -1, v193, vcc
	v_add_co_u32_e32 v66, vcc, 0xfffc0000, v192
	s_nop 1
	v_addc_co_u32_e32 v67, vcc, -1, v193, vcc
	global_load_dwordx4 v[164:167], v[64:65], off
	global_load_dwordx4 v[168:171], v[66:67], off
	v_add_co_u32_e32 v64, vcc, 0xffffe000, v188
	s_nop 1
	v_addc_co_u32_e32 v65, vcc, -1, v189, vcc
	global_load_dwordx4 v[172:175], v[64:65], off
	v_add_co_u32_e32 v64, vcc, 0xffdfff80, v190
	s_nop 1
	v_addc_co_u32_e32 v65, vcc, -1, v191, vcc
	v_add_co_u32_e32 v66, vcc, 0xffffff80, v190
	s_nop 1
	v_addc_co_u32_e32 v67, vcc, -1, v191, vcc
	global_load_dwordx4 v[176:179], v[64:65], off
	global_load_dwordx4 v[180:183], v[66:67], off
	s_waitcnt lgkmcnt(0)
	s_barrier
	s_branch .LBB0_33
.LBB0_32:
	s_mov_b64 s[40:41], 0x100
	v_lshl_add_u64 v[190:191], v[190:191], 0, s[40:41]
	s_mov_b64 s[40:41], 0x80000
	v_add_u32_e32 v219, 0x80, v219
	v_lshl_add_u64 v[188:189], v[188:189], 0, s[96:97]
	v_lshl_add_u64 v[192:193], v[192:193], 0, s[40:41]
	s_add_i32 s20, s20, 2
	s_waitcnt lgkmcnt(0)
	s_cmp_lt_u32 s20, s59
	s_cbranch_scc0 .Lattn_pfB1_skip
	v_add_co_u32_e32 v64, vcc, 0xfffa0000, v192
	s_nop 1
	v_addc_co_u32_e32 v65, vcc, -1, v193, vcc
	v_add_co_u32_e32 v66, vcc, 0xfffc0000, v192
	s_nop 1
	v_addc_co_u32_e32 v67, vcc, -1, v193, vcc
	global_load_dwordx4 v[164:167], v[64:65], off
	global_load_dwordx4 v[168:171], v[66:67], off
	v_add_co_u32_e32 v64, vcc, 0xffffe000, v188
	s_nop 1
	v_addc_co_u32_e32 v65, vcc, -1, v189, vcc
	global_load_dwordx4 v[172:175], v[64:65], off
	v_add_co_u32_e32 v64, vcc, 0xffdfff80, v190
	s_nop 1
	v_addc_co_u32_e32 v65, vcc, -1, v191, vcc
	v_add_co_u32_e32 v66, vcc, 0xffffff80, v190
	s_nop 1
	v_addc_co_u32_e32 v67, vcc, -1, v191, vcc
	global_load_dwordx4 v[176:179], v[64:65], off
	global_load_dwordx4 v[180:183], v[66:67], off
; #define LAS __attribute__((address_space(3)))
; #define MFMA32(a, b, c) __builtin_amdgcn_mfma_f32_32x32x16_bf16((a), (b), (c), 0, 0, 0)
; #define ATT_LOAD(kr, vr, t) do { const bf16_t* kp_ = KVb + (size_t)(t) * 64 * 2048 + kn_off; \
;         kr[0] = *(const u32x4*)kp_; kr[1] = *(const u32x4*)(kp_ + 32 * 2048); kr[2] = *(const u32x4*)(KPEb + (t) * 64 * 64 + kp_off); \
;         const bf16_t* vp_ = VTb + (t) * 64 + v_off; vr[0] = *(const u32x4*)vp_; vr[1] = *(const u32x4*)(vp_ + 64 * SEQ); } while (0)
; #define ATT_TILE(t, slot) do { const int rel_ = (t) - 4 * qb; if (rel_ <= (w >> 1)) { qk_softmax((t), (slot), rel_ == (w >> 1)); pv(slot); } } while (0)
; DI void attn_unit(const Params& P, LAS unsigned char* lds, int b, int h, int qb, bool dry) {
;     ...
;     auto qk_softmax = [&](int kt, int kslot, bool domask) {
;         const LAS unsigned char* kb_ = Ks + kslot * KS_BYTES + r * KS_STRIDE + 16 * hh;
;         f32x16 s0, s1;
;         __builtin_amdgcn_s_setprio(1);
;         { const f32x16 z16 = {0.f, 0.f, 0.f, 0.f, 0.f, 0.f, 0.f, 0.f, 0.f, 0.f, 0.f, 0.f, 0.f, 0.f, 0.f, 0.f};
;           const bf16x8 a0 = *(const LAS bf16x8*)(kb_), a1 = *(const LAS bf16x8*)(kb_ + 32 * KS_STRIDE);
;           s0 = MFMA32(a0, qf[0], z16); s1 = MFMA32(a1, qf[0], z16); }
; #pragma unroll
;         for (int s = 1; s < 12; ++s) {
;             const bf16x8 a0 = *(const LAS bf16x8*)(kb_ + 32 * s), a1 = *(const LAS bf16x8*)(kb_ + 32 * KS_STRIDE + 32 * s);
;             s0 = MFMA32(a0, qf[s], s0); s1 = MFMA32(a1, qf[s], s1);
;         }
;         __builtin_amdgcn_s_setprio(0);
;     ...
;     ATT_LOAD(kA, vA, 0);
;     __syncthreads();
;     ATT_STORE(kA, vA, 0);
;     ATT_LOAD(kA, vA, 1);
;     __syncthreads();
;     for (int kt = 0; kt < nt; kt += 2) {
;         const bool more2 = kt + 2 < nt;
;         if (more2) ATT_LOAD(kB, vB, kt + 2);
;         ATT_TILE(kt, 0);
.Lattn_pfB1_skip:
	s_andn2_b64 vcc, exec, s[50:51]
	s_barrier
	s_cbranch_vccz .LBB0_51
.LBB0_33:
	s_cmp_lt_u32 s20, s59
	s_cselect_b64 s[52:53], -1, 0
	s_cmp_ge_u32 s20, s59
	s_cselect_b64 s[50:51], -1, 0
	s_and_b64 vcc, exec, s[50:51]
	s_cbranch_vccnz .LBB0_35
.LBB0_35:
	s_add_i32 s80, s62, s20
	s_add_i32 s40, s80, -2
	s_cmp_gt_i32 s40, s26
	v_add_u32_e32 v220, v213, v184
	s_cbranch_scc1 .LBB0_41
	s_add_i32 s40, s63, s20
	s_cmp_lg_u32 s40, 2
	s_setprio 1
	ds_read_b128 v[222:225], v220
	ds_read_b128 v[226:229], v220 offset:12800
	ds_read_b128 v[230:233], v220 offset:32
	ds_read_b128 v[234:237], v220 offset:12832
	s_waitcnt lgkmcnt(3)
	v_mfma_f32_32x32x16_bf16 v[80:95], v[222:225], v[96:99], v[196:211]
	ds_read_b128 v[222:225], v220 offset:64
	s_waitcnt lgkmcnt(3)
	v_mfma_f32_32x32x16_bf16 v[64:79], v[226:229], v[96:99], v[196:211]
	ds_read_b128 v[226:229], v220 offset:12864
	s_waitcnt lgkmcnt(3)
	v_mfma_f32_32x32x16_bf16 v[80:95], v[230:233], v[100:103], v[80:95]
	ds_read_b128 v[230:233], v220 offset:96
	s_waitcnt lgkmcnt(3)
	v_mfma_f32_32x32x16_bf16 v[64:79], v[234:237], v[100:103], v[64:79]
	ds_read_b128 v[234:237], v220 offset:12896
	s_waitcnt lgkmcnt(3)
	v_mfma_f32_32x32x16_bf16 v[80:95], v[222:225], v[104:107], v[80:95]
	ds_read_b128 v[222:225], v220 offset:128
	s_waitcnt lgkmcnt(3)
	v_mfma_f32_32x32x16_bf16 v[64:79], v[226:229], v[104:107], v[64:79]
	ds_read_b128 v[226:229], v220 offset:12928
	s_waitcnt lgkmcnt(3)
	v_mfma_f32_32x32x16_bf16 v[80:95], v[230:233], v[108:111], v[80:95]
	ds_read_b128 v[230:233], v220 offset:160
	s_waitcnt lgkmcnt(3)
	v_mfma_f32_32x32x16_bf16 v[64:79], v[234:237], v[108:111], v[64:79]
	ds_read_b128 v[234:237], v220 offset:12960
	s_waitcnt lgkmcnt(3)
	v_mfma_f32_32x32x16_bf16 v[80:95], v[222:225], v[112:115], v[80:95]
	ds_read_b128 v[222:225], v220 offset:192
	s_waitcnt lgkmcnt(3)
	v_mfma_f32_32x32x16_bf16 v[64:79], v[226:229], v[112:115], v[64:79]
	ds_read_b128 v[226:229], v220 offset:12992
	s_waitcnt lgkmcnt(3)
	v_mfma_f32_32x32x16_bf16 v[80:95], v[230:233], v[116:119], v[80:95]
	ds_read_b128 v[230:233], v220 offset:224
	s_waitcnt lgkmcnt(3)
	v_mfma_f32_32x32x16_bf16 v[64:79], v[234:237], v[116:119], v[64:79]
	ds_read_b128 v[234:237], v220 offset:13024
	s_waitcnt lgkmcnt(3)
	v_mfma_f32_32x32x16_bf16 v[80:95], v[222:225], v[120:123], v[80:95]
	ds_read_b128 v[222:225], v220 offset:256
	s_waitcnt lgkmcnt(3)
	v_mfma_f32_32x32x16_bf16 v[64:79], v[226:229], v[120:123], v[64:79]
	ds_read_b128 v[226:229], v220 offset:13056
	s_waitcnt lgkmcnt(3)
	v_mfma_f32_32x32x16_bf16 v[80:95], v[230:233], v[124:127], v[80:95]
	ds_read_b128 v[230:233], v220 offset:288
	s_waitcnt lgkmcnt(3)
	v_mfma_f32_32x32x16_bf16 v[64:79], v[234:237], v[124:127], v[64:79]
	ds_read_b128 v[234:237], v220 offset:13088
	s_waitcnt lgkmcnt(3)
	v_mfma_f32_32x32x16_bf16 v[80:95], v[222:225], v[128:131], v[80:95]
	ds_read_b128 v[222:225], v220 offset:320
	s_waitcnt lgkmcnt(3)
	v_mfma_f32_32x32x16_bf16 v[64:79], v[226:229], v[128:131], v[64:79]
	ds_read_b128 v[226:229], v220 offset:13120
	s_waitcnt lgkmcnt(3)
	v_mfma_f32_32x32x16_bf16 v[80:95], v[230:233], v[132:135], v[80:95]
	ds_read_b128 v[230:233], v220 offset:352
	s_waitcnt lgkmcnt(3)
	v_mfma_f32_32x32x16_bf16 v[64:79], v[234:237], v[132:135], v[64:79]
	ds_read_b128 v[234:237], v220 offset:13152
	s_waitcnt lgkmcnt(3)
	v_mfma_f32_32x32x16_bf16 v[80:95], v[222:225], v[136:139], v[80:95]
	s_waitcnt lgkmcnt(2)
	v_mfma_f32_32x32x16_bf16 v[64:79], v[226:229], v[136:139], v[64:79]
	s_waitcnt lgkmcnt(1)
	v_mfma_f32_32x32x16_bf16 v[80:95], v[230:233], v[140:143], v[80:95]
	s_waitcnt lgkmcnt(0)
	v_mfma_f32_32x32x16_bf16 v[64:79], v[234:237], v[140:143], v[64:79]
	s_setprio 0
	s_nop 0
	s_mov_b64 vcc, s[52:53]
	s_cbranch_vccnz .Lattn_hw0_v5
	s_waitcnt vmcnt(0)
	s_branch .Lattn_hw0_go

; #define ATT_LOAD(kr, vr, t) do { const bf16_t* kp_ = KVb + (size_t)(t) * 64 * 2048 + kn_off; \
;         kr[0] = *(const u32x4*)kp_; kr[1] = *(const u32x4*)(kp_ + 32 * 2048); kr[2] = *(const u32x4*)(KPEb + (t) * 64 * 64 + kp_off); \
;         const bf16_t* vp_ = VTb + (t) * 64 + v_off; vr[0] = *(const u32x4*)vp_; vr[1] = *(const u32x4*)(vp_ + 64 * SEQ); } while (0)
; #define ATT_TILE(t, slot) do { const int rel_ = (t) - 4 * qb; if (rel_ <= (w >> 1)) { qk_softmax((t), (slot), rel_ == (w >> 1)); pv(slot); } } while (0)
; DI void attn_unit(const Params& P, LAS unsigned char* lds, int b, int h, int qb, bool dry) {
;     ...
;     ATT_LOAD(kA, vA, 0);
;     __syncthreads();
;     ATT_STORE(kA, vA, 0);
;     ATT_LOAD(kA, vA, 1);
;     __syncthreads();
;     for (int kt = 0; kt < nt; kt += 2) {
;         const bool more2 = kt + 2 < nt;
;         if (more2) ATT_LOAD(kB, vB, kt + 2);
;         ATT_TILE(kt, 0);
;         ATT_STORE(kA, vA, 1);
;         __syncthreads();
;         if (more2) ATT_LOAD(kA, vA, kt + 3);
;         ATT_TILE(kt + 1, 1);
.Lattn_wdone0:
	s_not_b64 s[40:41], s[52:53]
	s_waitcnt lgkmcnt(0)
	s_mov_b64 vcc, s[52:53]
	s_cbranch_vccz .Lattn_pfA1_skip
	v_add_co_u32_e32 v64, vcc, 0xfffe0000, v192
	s_nop 1
	v_addc_co_u32_e32 v65, vcc, -1, v193, vcc
	global_load_dwordx4 v[144:147], v[64:65], off
	global_load_dwordx4 v[148:151], v[192:193], off
	global_load_dwordx4 v[152:155], v[188:189], off
	v_add_co_u32_e32 v64, vcc, 0xffe00000, v190
	s_nop 1
	v_addc_co_u32_e32 v65, vcc, -1, v191, vcc
	global_load_dwordx4 v[156:159], v[64:65], off
	global_load_dwordx4 v[160:163], v[190:191], off
.Lattn_pfA1_skip:
	s_andn2_b64 vcc, exec, s[52:53]
	s_barrier
	s_cbranch_vccnz .LBB0_44
	s_add_i32 s80, s80, -1
	s_cmp_gt_i32 s80, s26
	s_cbranch_scc0 .LBB0_45

; #define LAS __attribute__((address_space(3)))
; DI unsigned pk_bf16(float lo, float hi) { unsigned r; asm("v_cvt_pk_bf16_f32 %0, %1, %2" : "=v"(r) : "v"(lo), "v"(hi)); return r; }
; DI int obid() { int b = blockIdx.x; asm volatile("" : "+s"(b)); return b; }
; DI void attn_unit(const Params& P, LAS unsigned char* lds, int b, int h, int qb, bool dry) {
;     ...
;     float lt; { const auto rr = __builtin_amdgcn_permlane32_swap(__float_as_uint(lrun), __float_as_uint(lrun), false, false); lt = __uint_as_float(rr[0]) + __uint_as_float(rr[1]); }
;     const float inv = 1.f / lt;
;     if (dry) { float tt = 0.f;
; #pragma unroll
;         for (int d = 0; d < 4; ++d)
; #pragma unroll
;             for (int i = 0; i < 16; ++i) tt += o[d][i];
;         if (tt * inv != 123456.789f) return; }
; #pragma unroll
;     for (int d = 0; d < 4; ++d)
; #pragma unroll
;         for (int g = 0; g < 4; ++g) {
;             u32x2 ov; ov.x = pk_bf16(o[d][4 * g] * inv, o[d][4 * g + 1] * inv); ov.y = pk_bf16(o[d][4 * g + 2] * inv, o[d][4 * g + 3] * inv);
;             *(u32x2*)(qrow + 32 * d + 8 * g + 4 * hh) = ov;
;         }
; }
; DI void phase_attn(const Params& P, LAS unsigned char* lds, bool dry) {
;     for (int item = obid(); item < 512; item += gridDim.x) {
;         const int h = item & 7, p = (item >> 3) & 31, b = item >> 8;
;         attn_unit(P, lds, b, h, 63 - p, dry);
.LBB0_51:
	v_mov_b32_e32 v64, v215
	s_nop 1
	v_permlane32_swap_b32_e32 v215, v64
	v_add_f32_e32 v64, v215, v64
	v_div_scale_f32 v65, s[26:27], v64, v64, 1.0
	v_rcp_f32_e32 v66, v65
	v_lshlrev_b32_e32 v184, 1, v212
	s_and_b32 s20, s56, 31
	s_lshl_b32 s53, s20, 2
	v_fma_f32 v67, -v65, v66, 1.0
	v_fmac_f32_e32 v66, v67, v66
	v_div_scale_f32 v67, vcc, 1.0, v64, 1.0
	v_mul_f32_e32 v68, v67, v66
	v_fma_f32 v69, -v65, v68, v67
	v_fmac_f32_e32 v68, v69, v66
	v_fma_f32 v65, -v65, v68, v67
	v_div_fmas_f32 v65, v65, v66, v68
	v_div_fixup_f32 v66, v65, v64, 1.0
	v_mul_f32_e32 v32, v32, v66
	v_mul_f32_e32 v33, v33, v66
	v_mul_f32_e32 v48, v48, v66
	v_mul_f32_e32 v49, v49, v66
	v_cvt_pk_bf16_f32 v32, v32, v33
	v_mul_f32_e32 v33, v34, v66
	v_mul_f32_e32 v16, v16, v66
	v_mul_f32_e32 v17, v17, v66
	v_mul_f32_e32 v0, v0, v66
	v_mul_f32_e32 v1, v1, v66
	v_lshl_add_u64 v[64:65], v[186:187], 0, v[184:185]
	v_cvt_pk_bf16_f32 v48, v48, v49
	v_mul_f32_e32 v49, v50, v66
	v_mul_f32_e32 v34, v35, v66
	v_cvt_pk_bf16_f32 v33, v33, v34
	v_cvt_pk_bf16_f32 v16, v16, v17
	v_mul_f32_e32 v17, v18, v66
	v_cvt_pk_bf16_f32 v0, v0, v1
	v_mul_f32_e32 v1, v2, v66
	v_mul_f32_e32 v50, v51, v66
	v_cvt_pk_bf16_f32 v49, v49, v50
	global_store_dwordx2 v[64:65], v[32:33], off offset:64
	v_mul_f32_e32 v32, v36, v66
	v_mul_f32_e32 v33, v37, v66
	v_mul_f32_e32 v18, v19, v66
	v_cvt_pk_bf16_f32 v17, v17, v18
	v_mul_f32_e32 v2, v3, v66
	v_cvt_pk_bf16_f32 v1, v1, v2
	global_store_dwordx2 v[64:65], v[48:49], off
	v_mul_f32_e32 v48, v52, v66
	v_mul_f32_e32 v49, v53, v66
	v_cvt_pk_bf16_f32 v32, v32, v33
	v_mul_f32_e32 v33, v38, v66
	global_store_dwordx2 v[64:65], v[16:17], off offset:128
	v_mul_f32_e32 v16, v20, v66
	v_mul_f32_e32 v17, v21, v66
	global_store_dwordx2 v[64:65], v[0:1], off offset:192
	v_mul_f32_e32 v0, v4, v66
	v_mul_f32_e32 v1, v5, v66
	v_cvt_pk_bf16_f32 v48, v48, v49
	v_mul_f32_e32 v49, v54, v66
	v_mul_f32_e32 v34, v39, v66
	v_cvt_pk_bf16_f32 v33, v33, v34
	v_cvt_pk_bf16_f32 v16, v16, v17
	v_mul_f32_e32 v17, v22, v66
	v_cvt_pk_bf16_f32 v0, v0, v1
	v_mul_f32_e32 v1, v6, v66
	v_mul_f32_e32 v50, v55, v66
	v_cvt_pk_bf16_f32 v49, v49, v50
	global_store_dwordx2 v[64:65], v[32:33], off offset:80
	v_mul_f32_e32 v32, v40, v66
	v_mul_f32_e32 v33, v41, v66
	v_mul_f32_e32 v18, v23, v66
	v_cvt_pk_bf16_f32 v17, v17, v18
	v_mul_f32_e32 v2, v7, v66
	v_cvt_pk_bf16_f32 v1, v1, v2
	global_store_dwordx2 v[64:65], v[48:49], off offset:16
	v_mul_f32_e32 v48, v56, v66
	v_mul_f32_e32 v49, v57, v66
	v_cvt_pk_bf16_f32 v32, v32, v33
	v_mul_f32_e32 v33, v42, v66
	global_store_dwordx2 v[64:65], v[16:17], off offset:144
	v_mul_f32_e32 v16, v24, v66
	v_mul_f32_e32 v17, v25, v66
	global_store_dwordx2 v[64:65], v[0:1], off offset:208
	v_mul_f32_e32 v0, v8, v66
	v_mul_f32_e32 v1, v9, v66
	v_cvt_pk_bf16_f32 v48, v48, v49
	v_mul_f32_e32 v49, v58, v66
	v_mul_f32_e32 v34, v43, v66
	v_cvt_pk_bf16_f32 v33, v33, v34
	v_cvt_pk_bf16_f32 v16, v16, v17
	v_mul_f32_e32 v17, v26, v66
	v_cvt_pk_bf16_f32 v0, v0, v1
	v_mul_f32_e32 v1, v10, v66
	v_mul_f32_e32 v50, v59, v66
	v_cvt_pk_bf16_f32 v49, v49, v50
	global_store_dwordx2 v[64:65], v[32:33], off offset:96
	v_mul_f32_e32 v32, v44, v66
	v_mul_f32_e32 v33, v45, v66
	v_mul_f32_e32 v18, v27, v66
	v_cvt_pk_bf16_f32 v17, v17, v18
	v_mul_f32_e32 v2, v11, v66
	v_cvt_pk_bf16_f32 v1, v1, v2
	global_store_dwordx2 v[64:65], v[48:49], off offset:32
	v_mul_f32_e32 v48, v60, v66
	v_mul_f32_e32 v49, v61, v66
	v_cvt_pk_bf16_f32 v32, v32, v33
	v_mul_f32_e32 v33, v46, v66
	global_store_dwordx2 v[64:65], v[16:17], off offset:160
	v_mul_f32_e32 v16, v28, v66
	v_mul_f32_e32 v17, v29, v66
	global_store_dwordx2 v[64:65], v[0:1], off offset:224
	v_mul_f32_e32 v0, v12, v66
	v_mul_f32_e32 v1, v13, v66
	v_cvt_pk_bf16_f32 v48, v48, v49
	v_mul_f32_e32 v49, v62, v66
	v_mul_f32_e32 v34, v47, v66
	v_cvt_pk_bf16_f32 v33, v33, v34
	global_store_dwordx2 v[64:65], v[32:33], off offset:112
	v_cvt_pk_bf16_f32 v16, v16, v17
	v_mul_f32_e32 v17, v30, v66
	v_cvt_pk_bf16_f32 v0, v0, v1
	v_mul_f32_e32 v1, v14, v66
	v_mov_b32_e32 v32, v195
	v_mul_f32_e32 v50, v63, v66
	v_cvt_pk_bf16_f32 v49, v49, v50
	global_store_dwordx2 v[64:65], v[48:49], off offset:48
	v_mul_f32_e32 v18, v31, v66
	v_cvt_pk_bf16_f32 v17, v17, v18
	global_store_dwordx2 v[64:65], v[16:17], off offset:176
	v_mul_f32_e32 v2, v15, v66
	v_cvt_pk_bf16_f32 v1, v1, v2
	global_store_dwordx2 v[64:65], v[0:1], off offset:240
	s_load_dwordx8 s[60:67], s[84:85], 0xc8
	v_readfirstlane_b32 s42, v32
	s_ashr_i32 s43, s42, 1
	s_lshl_b32 s20, s35, 8
	s_andn2_b32 s43, s43, 31
	s_add_i32 s43, s43, s20
	s_sub_i32 s52, 0, s53
	s_ashr_i32 s20, s43, 31
	s_add_u32 s56, s2, s43
	s_addc_u32 s59, s3, s20
	s_lshl_b32 s35, s35, 2
	s_waitcnt lgkmcnt(0)
; #define LAS __attribute__((address_space(3)))
; DI int otid() { int t = threadIdx.x; asm volatile("" : "+v"(t)); return t; }
; DI unsigned char* ows(const Params& P) { unsigned char* p = P.ws; asm volatile("" : "+s"(p)); return p; }
; #define ATT_LOAD(kr, vr, t) do { const bf16_t* kp_ = KVb + (size_t)(t) * 64 * 2048 + kn_off; \
;         kr[0] = *(const u32x4*)kp_; kr[1] = *(const u32x4*)(kp_ + 32 * 2048); kr[2] = *(const u32x4*)(KPEb + (t) * 64 * 64 + kp_off); \
;         const bf16_t* vp_ = VTb + (t) * 64 + v_off; vr[0] = *(const u32x4*)vp_; vr[1] = *(const u32x4*)(vp_ + 64 * SEQ); } while (0)
; DI void attn_unit(const Params& P, LAS unsigned char* lds, int b, int h, int qb, bool dry) {
;     const int tid = otid(), lane = tid & 63, w = __builtin_amdgcn_readfirstlane(tid >> 6), r = lane & 31, hh = lane >> 5;
;     bf16_t* Q = (bf16_t*)(ows(P) + OFF_Q);
;     const bf16_t* KV = (const bf16_t*)(ows(P) + OFF_KV); const bf16_t* KPE = (const bf16_t*)(ows(P) + OFF_KPE); const bf16_t* VT = (const bf16_t*)(ows(P) + OFF_U);
;     LAS unsigned char* Ks = lds; LAS unsigned char* Vs = lds + 2 * KS_BYTES;
;     const int q0 = qb * 256 + w * 32;
;     bf16_t* qrow = Q + ((size_t)b * SEQ + q0 + r) * 1536 + h * 192;
;     bf16x8 qf[12];
; #pragma unroll
;     for (int s = 0; s < 12; ++s) qf[s] = *(const bf16x8*)(qrow + 16 * s + 8 * hh);
;     f32x16 o[4];
; #pragma unroll
;     for (int d = 0; d < 4; ++d)
; #pragma unroll
;         for (int i = 0; i < 16; ++i) o[d][i] = 0.f;
;     float mrun = -INFINITY, lrun = 0.f;
;     const int nt = 4 * (qb + 1);
;     const bf16_t* KVb = KV + (size_t)b * SEQ * 2048 + h * 256; const bf16_t* KPEb = KPE + (size_t)b * SEQ * 64; const bf16_t* VTb = VT + (size_t)(b * 8 + h) * 128 * SEQ;
;     const int kn_off = (tid >> 4) * 2048 + (tid & 15) * 8, kn_dst = (tid >> 4) * KS_STRIDE + (tid & 15) * 16;
;     const int kp_off = (tid >> 3) * 64 + (tid & 7) * 8, kp_dst = (tid >> 3) * KS_STRIDE + 256 + (tid & 7) * 16;
;     const int v_off = (tid >> 3) * SEQ + (tid & 7) * 8, v_dst = (tid >> 3) * VS_STRIDE + (tid & 7) * 16;
;     ...
;     ATT_LOAD(kA, vA, 0);
;     __syncthreads();
;     ATT_STORE(kA, vA, 0);
;     ATT_LOAD(kA, vA, 1);
;     __syncthreads();
	s_mov_b64 s[50:51], s[66:67]
	s_mov_b64 s[26:27], s[66:67]
	s_lshl_b32 s20, s36, 1
	s_add_i32 s35, s35, 4
	v_and_b32_e32 v35, 15, v32
	s_add_u32 s2, s26, s44
	v_ashrrev_i32_e32 v34, 4, v32
	v_lshlrev_b32_e32 v0, 3, v35
	v_and_b32_e32 v37, 7, v32
	s_addc_u32 s3, s27, s45
	s_lshl_b32 s36, s37, 1
	v_lshl_or_b32 v0, v34, 11, v0
	v_ashrrev_i32_e32 v36, 3, v32
	v_lshlrev_b32_e32 v1, 3, v37
	s_add_u32 s2, s2, s36
	v_lshl_or_b32 v8, v36, 6, v1
	v_lshl_or_b32 v12, v36, 14, v1
	v_ashrrev_i32_e32 v1, 31, v0
	s_addc_u32 s3, s3, 0
	v_lshlrev_b64 v[20:21], 1, v[0:1]
	s_mov_b64 s[62:63], s[66:67]
	s_mov_b64 s[40:41], s[66:67]
	v_lshl_add_u64 v[22:23], s[2:3], 0, v[20:21]
	s_mov_b32 s2, 0x13808000
	s_add_u32 s36, s40, s46
	v_add_co_u32_e32 v0, vcc, s2, v22
	s_addc_u32 s37, s41, s47
	s_nop 0
	v_addc_co_u32_e32 v1, vcc, 0, v23, vcc
	s_mov_b32 s2, 0x13828000
	v_add_co_u32_e32 v4, vcc, s2, v22
	s_add_u32 s2, s62, s30
	v_ashrrev_i32_e32 v9, 31, v8
	s_addc_u32 s3, s63, s31
	v_addc_co_u32_e32 v5, vcc, 0, v23, vcc
	v_lshl_add_u64 v[24:25], v[8:9], 1, s[2:3]
	s_mov_b32 s2, 0xd408000
	v_ashrrev_i32_e32 v13, 31, v12
	v_add_co_u32_e32 v8, vcc, s2, v24
	v_lshlrev_b64 v[26:27], 1, v[12:13]
	global_load_dwordx4 v[0:3], v[0:1], off
	s_nop 0
	global_load_dwordx4 v[4:7], v[4:5], off
	v_addc_co_u32_e32 v9, vcc, 0, v25, vcc
	v_lshl_add_u64 v[28:29], s[36:37], 0, v[26:27]
	s_mov_b32 s2, 0x5808000
	v_add_co_u32_e32 v12, vcc, s2, v28
	s_mov_b32 s2, 0x5a08000
	s_nop 0
	v_addc_co_u32_e32 v13, vcc, 0, v29, vcc
	v_add_co_u32_e32 v30, vcc, s2, v28
	global_load_dwordx4 v[8:11], v[8:9], off
	s_nop 0
	v_addc_co_u32_e32 v31, vcc, 0, v29, vcc
	global_load_dwordx4 v[12:15], v[12:13], off
	v_and_b32_e32 v38, 31, v32
	global_load_dwordx4 v[16:19], v[30:31], off
	v_bfe_u32 v39, v32, 5, 1
	v_or_b32_e32 v40, s56, v38
	v_mov_b64_e32 v[32:33], s[50:51]
	v_mad_u64_u32 v[32:33], s[2:3], v40, s39, v[32:33]
	v_mad_i32_i24 v33, s59, v248, v33
	v_lshl_add_u64 v[32:33], v[32:33], 0, s[20:21]
	s_mov_b64 s[2:3], 0xd808000
	v_lshl_add_u64 v[186:187], v[32:33], 0, s[2:3]
	v_lshlrev_b32_e32 v184, 4, v39
	v_lshl_add_u64 v[32:33], v[186:187], 0, v[184:185]
	global_load_dwordx4 v[96:99], v[32:33], off
	global_load_dwordx4 v[100:103], v[32:33], off offset:32
	global_load_dwordx4 v[104:107], v[32:33], off offset:64
	global_load_dwordx4 v[108:111], v[32:33], off offset:96
	global_load_dwordx4 v[112:115], v[32:33], off offset:128
	global_load_dwordx4 v[116:119], v[32:33], off offset:160
	global_load_dwordx4 v[120:123], v[32:33], off offset:192
	global_load_dwordx4 v[124:127], v[32:33], off offset:224
	global_load_dwordx4 v[128:131], v[32:33], off offset:256
	global_load_dwordx4 v[132:135], v[32:33], off offset:288
	global_load_dwordx4 v[136:139], v[32:33], off offset:320
	global_load_dwordx4 v[140:143], v[32:33], off offset:352
	v_mul_lo_u32 v32, v34, s29
	v_lshl_add_u32 v33, v35, 4, v32
	v_lshlrev_b32_e32 v32, 4, v37
	v_mad_u64_u32 v[34:35], s[2:3], v36, s68, v[32:33]
	s_mov_b64 s[2:3], 0x5808000
	s_nop 0
	v_lshl_add_u64 v[28:29], v[28:29], 0, s[2:3]
	v_add_u32_e32 v250, 0, v33
	s_movk_i32 s2, 0x108
	s_waitcnt lgkmcnt(0)
	s_barrier
	s_waitcnt vmcnt(0)
	ds_write_b128 v250, v[0:3]
	ds_write_b128 v250, v[4:7] offset:12800
	v_mad_u64_u32 v[0:1], s[2:3], v36, s2, v[34:35]
	s_mov_b32 s2, 0x13848000
	v_add_u32_e32 v251, 0, v0
	v_add_co_u32_e32 v0, vcc, s2, v22
	v_add_u32_e32 v252, 0, v34
	s_nop 0
	v_addc_co_u32_e32 v1, vcc, 0, v23, vcc
	s_mov_b32 s2, 0x13868000
	v_add_u32_e32 v253, 0xc800, v252
	v_add_u32_e32 v254, 0xea00, v252
	v_add_co_u32_e32 v2, vcc, s2, v22
	ds_write_b128 v251, v[8:11] offset:256
	ds_write2_b64 v253, v[12:13], v[14:15] offset1:1
	ds_write2_b64 v254, v[16:17], v[18:19] offset1:1
	v_addc_co_u32_e32 v3, vcc, 0, v23, vcc
	s_mov_b32 s2, 0xd40a000
	global_load_dwordx4 v[144:147], v[0:1], off
	global_load_dwordx4 v[148:151], v[2:3], off
	v_add_co_u32_e32 v0, vcc, s2, v24
	v_mad_u32_u24 v213, v38, s29, 0
	s_nop 0
	v_addc_co_u32_e32 v1, vcc, 0, v25, vcc
	global_load_dwordx4 v[152:155], v[0:1], off
	global_load_dwordx4 v[156:159], v[28:29], off offset:128
	global_load_dwordx4 v[160:163], v[30:31], off offset:128
	s_movk_i32 s2, 0xfef8
	v_mad_i32_i24 v19, v38, s2, v213
	v_mad_u64_u32 v[16:17], s[2:3], v36, s29, v[32:33]
	v_readlane_b32 s2, v246, 47
	s_ashr_i32 s36, s42, 7
	v_lshlrev_b32_e32 v18, 3, v39
	v_mov_b32_e32 v0, s2
	s_mov_b64 s[2:3], 0xd40e000
	v_lshl_add_u64 v[188:189], v[24:25], 0, s[2:3]
	s_add_u32 s2, s40, s48
	s_addc_u32 s3, s41, s49
	v_mad_u32_u24 v17, v38, s68, v0
	v_lshl_add_u64 v[0:1], s[2:3], 0, v[26:27]
	s_mov_b64 s[2:3], 0x5a08180
	v_lshl_add_u64 v[190:191], v[0:1], 0, s[2:3]
	s_add_u32 s2, s26, s57
	s_addc_u32 s3, s27, s58
	v_lshl_add_u64 v[0:1], s[2:3], 0, v[20:21]
	s_mov_b64 s[2:3], 0x138e8000
	v_mov_b32_e32 v14, v185
	v_mov_b32_e32 v15, v185
	v_or_b32_e32 v214, s43, v38
	v_lshlrev_b32_e32 v212, 2, v39
	v_lshl_add_u64 v[192:193], v[0:1], 0, s[2:3]
	s_add_i32 s2, s36, s53
	v_mov_b32_e32 v0, v185
	v_mov_b32_e32 v1, v185
	v_mov_b32_e32 v2, v185
	v_mov_b32_e32 v3, v185
	v_mov_b32_e32 v4, v185
	v_mov_b32_e32 v5, v185
	v_mov_b32_e32 v6, v185
	v_mov_b32_e32 v7, v185
	v_mov_b32_e32 v8, v185
	v_mov_b32_e32 v9, v185
	v_mov_b32_e32 v10, v185
	v_mov_b32_e32 v11, v185
	v_mov_b32_e32 v12, v185
	v_mov_b32_e32 v13, v185
	v_add_u32_e32 v216, v19, v18
	v_add_u32_e32 v217, 0, v16
	v_add_u32_e32 v218, v17, v18
	v_mov_b64_e32 v[30:31], v[14:15]
	v_mov_b64_e32 v[46:47], v[14:15]
	v_mov_b64_e32 v[62:63], v[14:15]
	s_mov_b32 s20, 2
	s_sub_i32 s26, 1, s2
	s_sub_i32 s27, 0, s2
	v_mov_b32_e32 v194, 0xff800000
	v_mov_b32_e32 v196, 0
	v_mov_b32_e32 v197, 0
	v_mov_b32_e32 v198, 0
	v_mov_b32_e32 v199, 0
; #define LAS __attribute__((address_space(3)))
; #define MFMA32(a, b, c) __builtin_amdgcn_mfma_f32_32x32x16_bf16((a), (b), (c), 0, 0, 0)
; #define ATT_LOAD(kr, vr, t) do { const bf16_t* kp_ = KVb + (size_t)(t) * 64 * 2048 + kn_off; \
;         kr[0] = *(const u32x4*)kp_; kr[1] = *(const u32x4*)(kp_ + 32 * 2048); kr[2] = *(const u32x4*)(KPEb + (t) * 64 * 64 + kp_off); \
;         const bf16_t* vp_ = VTb + (t) * 64 + v_off; vr[0] = *(const u32x4*)vp_; vr[1] = *(const u32x4*)(vp_ + 64 * SEQ); } while (0)
; #define ATT_TILE(t, slot) do { const int rel_ = (t) - 4 * qb; if (rel_ <= (w >> 1)) { qk_softmax((t), (slot), rel_ == (w >> 1)); pv(slot); } } while (0)
; DI void attn_unit(const Params& P, LAS unsigned char* lds, int b, int h, int qb, bool dry) {
;     ...
;     auto qk_softmax = [&](int kt, int kslot, bool domask) {
;         const LAS unsigned char* kb_ = Ks + kslot * KS_BYTES + r * KS_STRIDE + 16 * hh;
;         f32x16 s0, s1;
;         __builtin_amdgcn_s_setprio(1);
;         { const f32x16 z16 = {0.f, 0.f, 0.f, 0.f, 0.f, 0.f, 0.f, 0.f, 0.f, 0.f, 0.f, 0.f, 0.f, 0.f, 0.f, 0.f};
;           const bf16x8 a0 = *(const LAS bf16x8*)(kb_), a1 = *(const LAS bf16x8*)(kb_ + 32 * KS_STRIDE);
;           s0 = MFMA32(a0, qf[0], z16); s1 = MFMA32(a1, qf[0], z16); }
; #pragma unroll
;         for (int s = 1; s < 12; ++s) {
;             const bf16x8 a0 = *(const LAS bf16x8*)(kb_ + 32 * s), a1 = *(const LAS bf16x8*)(kb_ + 32 * KS_STRIDE + 32 * s);
;             s0 = MFMA32(a0, qf[s], s0); s1 = MFMA32(a1, qf[s], s1);
;         }
;         __builtin_amdgcn_s_setprio(0);
;     ...
;     ATT_LOAD(kA, vA, 0);
;     __syncthreads();
;     ATT_STORE(kA, vA, 0);
;     ATT_LOAD(kA, vA, 1);
;     __syncthreads();
;     for (int kt = 0; kt < nt; kt += 2) {
;         const bool more2 = kt + 2 < nt;
;         if (more2) ATT_LOAD(kB, vB, kt + 2);
;         ATT_TILE(kt, 0);
	v_mov_b32_e32 v200, 0
	v_mov_b32_e32 v201, 0
	v_mov_b32_e32 v202, 0
	v_mov_b32_e32 v203, 0
	v_mov_b32_e32 v204, 0
	v_mov_b32_e32 v205, 0
	v_mov_b32_e32 v206, 0
	v_mov_b32_e32 v207, 0
	v_mov_b32_e32 v208, 0
	v_mov_b32_e32 v209, 0
	v_mov_b32_e32 v210, 0
	v_mov_b32_e32 v211, 0
	v_mov_b32_e32 v215, 0
	v_mov_b32_e32 v219, v212
	v_mov_b64_e32 v[28:29], v[12:13]
	v_mov_b64_e32 v[26:27], v[10:11]
	v_mov_b64_e32 v[24:25], v[8:9]
	v_mov_b64_e32 v[22:23], v[6:7]
	v_mov_b64_e32 v[20:21], v[4:5]
	v_mov_b64_e32 v[18:19], v[2:3]
	v_mov_b64_e32 v[16:17], v[0:1]
	v_mov_b64_e32 v[44:45], v[12:13]
	v_mov_b64_e32 v[42:43], v[10:11]
	v_mov_b64_e32 v[40:41], v[8:9]
	v_mov_b64_e32 v[38:39], v[6:7]
	v_mov_b64_e32 v[36:37], v[4:5]
	v_mov_b64_e32 v[34:35], v[2:3]
	v_mov_b64_e32 v[32:33], v[0:1]
	v_mov_b64_e32 v[60:61], v[12:13]
	v_mov_b64_e32 v[58:59], v[10:11]
	v_mov_b64_e32 v[56:57], v[8:9]
	v_mov_b64_e32 v[54:55], v[6:7]
	v_mov_b64_e32 v[52:53], v[4:5]
	v_mov_b64_e32 v[50:51], v[2:3]
	v_mov_b64_e32 v[48:49], v[0:1]
	s_mov_b64 s[60:61], 0
	v_add_co_u32_e32 v64, vcc, 0xfffa0000, v192
	s_nop 1
	v_addc_co_u32_e32 v65, vcc, -1, v193, vcc
	v_add_co_u32_e32 v66, vcc, 0xfffc0000, v192
	s_nop 1
	v_addc_co_u32_e32 v67, vcc, -1, v193, vcc
	global_load_dwordx4 v[164:167], v[64:65], off
	global_load_dwordx4 v[168:171], v[66:67], off
	v_add_co_u32_e32 v64, vcc, 0xffffe000, v188
	s_nop 1
	v_addc_co_u32_e32 v65, vcc, -1, v189, vcc
	global_load_dwordx4 v[172:175], v[64:65], off
	v_add_co_u32_e32 v64, vcc, 0xffdfff80, v190
	s_nop 1
	v_addc_co_u32_e32 v65, vcc, -1, v191, vcc
	v_add_co_u32_e32 v66, vcc, 0xffffff80, v190
	s_nop 1
	v_addc_co_u32_e32 v67, vcc, -1, v191, vcc
	global_load_dwordx4 v[176:179], v[64:65], off
	global_load_dwordx4 v[180:183], v[66:67], off
	s_waitcnt lgkmcnt(0)
	s_barrier
	s_branch .LBB0_53
.LBB0_52:
	s_mov_b64 s[30:31], 0x100
	v_lshl_add_u64 v[190:191], v[190:191], 0, s[30:31]
	s_mov_b64 s[30:31], 0x80000
	v_add_u32_e32 v219, 0x80, v219
	v_lshl_add_u64 v[188:189], v[188:189], 0, s[96:97]
	v_lshl_add_u64 v[192:193], v[192:193], 0, s[30:31]
	s_add_i32 s20, s20, 2
	s_waitcnt lgkmcnt(0)
	s_cmp_lt_u32 s20, s35
	s_cbranch_scc0 .Lattn_pfB2_skip
	v_add_co_u32_e32 v64, vcc, 0xfffa0000, v192
	s_nop 1
	v_addc_co_u32_e32 v65, vcc, -1, v193, vcc
	v_add_co_u32_e32 v66, vcc, 0xfffc0000, v192
	s_nop 1
	v_addc_co_u32_e32 v67, vcc, -1, v193, vcc
	global_load_dwordx4 v[164:167], v[64:65], off
	global_load_dwordx4 v[168:171], v[66:67], off
	v_add_co_u32_e32 v64, vcc, 0xffffe000, v188
	s_nop 1
	v_addc_co_u32_e32 v65, vcc, -1, v189, vcc
	global_load_dwordx4 v[172:175], v[64:65], off
	v_add_co_u32_e32 v64, vcc, 0xffdfff80, v190
	s_nop 1
	v_addc_co_u32_e32 v65, vcc, -1, v191, vcc
	v_add_co_u32_e32 v66, vcc, 0xffffff80, v190
	s_nop 1
	v_addc_co_u32_e32 v67, vcc, -1, v191, vcc
	global_load_dwordx4 v[176:179], v[64:65], off
	global_load_dwordx4 v[180:183], v[66:67], off
.Lattn_pfB2_skip:
	s_andn2_b64 vcc, exec, s[2:3]
	s_barrier
	s_cbranch_vccz .LBB0_30
.LBB0_53:
	s_cmp_lt_u32 s20, s35
	s_cselect_b64 s[30:31], -1, 0
	s_cmp_ge_u32 s20, s35
	s_cselect_b64 s[2:3], -1, 0
	s_and_b64 vcc, exec, s[2:3]
	s_cbranch_vccnz .LBB0_55
.LBB0_55:
	s_add_i32 s37, s52, s20
	s_add_i32 s40, s37, -2
	s_cmp_gt_i32 s40, s36
	v_add_u32_e32 v220, v213, v184
	s_cbranch_scc1 .LBB0_61
	s_add_i32 s40, s27, s20
	s_cmp_lg_u32 s40, 2
	s_setprio 1
	ds_read_b128 v[222:225], v220
	ds_read_b128 v[226:229], v220 offset:12800
	ds_read_b128 v[230:233], v220 offset:32
	ds_read_b128 v[234:237], v220 offset:12832
	s_waitcnt lgkmcnt(3)
	v_mfma_f32_32x32x16_bf16 v[80:95], v[222:225], v[96:99], v[196:211]
	ds_read_b128 v[222:225], v220 offset:64
	s_waitcnt lgkmcnt(3)
	v_mfma_f32_32x32x16_bf16 v[64:79], v[226:229], v[96:99], v[196:211]
	ds_read_b128 v[226:229], v220 offset:12864
	s_waitcnt lgkmcnt(3)
	v_mfma_f32_32x32x16_bf16 v[80:95], v[230:233], v[100:103], v[80:95]
	ds_read_b128 v[230:233], v220 offset:96
	s_waitcnt lgkmcnt(3)
	v_mfma_f32_32x32x16_bf16 v[64:79], v[234:237], v[100:103], v[64:79]
	ds_read_b128 v[234:237], v220 offset:12896
	s_waitcnt lgkmcnt(3)
	v_mfma_f32_32x32x16_bf16 v[80:95], v[222:225], v[104:107], v[80:95]
	ds_read_b128 v[222:225], v220 offset:128
	s_waitcnt lgkmcnt(3)
	v_mfma_f32_32x32x16_bf16 v[64:79], v[226:229], v[104:107], v[64:79]
	ds_read_b128 v[226:229], v220 offset:12928
	s_waitcnt lgkmcnt(3)
	v_mfma_f32_32x32x16_bf16 v[80:95], v[230:233], v[108:111], v[80:95]
	ds_read_b128 v[230:233], v220 offset:160
	s_waitcnt lgkmcnt(3)
	v_mfma_f32_32x32x16_bf16 v[64:79], v[234:237], v[108:111], v[64:79]
	ds_read_b128 v[234:237], v220 offset:12960
	s_waitcnt lgkmcnt(3)
	v_mfma_f32_32x32x16_bf16 v[80:95], v[222:225], v[112:115], v[80:95]
	ds_read_b128 v[222:225], v220 offset:192
	s_waitcnt lgkmcnt(3)
	v_mfma_f32_32x32x16_bf16 v[64:79], v[226:229], v[112:115], v[64:79]
	ds_read_b128 v[226:229], v220 offset:12992
	s_waitcnt lgkmcnt(3)
	v_mfma_f32_32x32x16_bf16 v[80:95], v[230:233], v[116:119], v[80:95]
	ds_read_b128 v[230:233], v220 offset:224
	s_waitcnt lgkmcnt(3)
	v_mfma_f32_32x32x16_bf16 v[64:79], v[234:237], v[116:119], v[64:79]
	ds_read_b128 v[234:237], v220 offset:13024
	s_waitcnt lgkmcnt(3)
	v_mfma_f32_32x32x16_bf16 v[80:95], v[222:225], v[120:123], v[80:95]
	ds_read_b128 v[222:225], v220 offset:256
	s_waitcnt lgkmcnt(3)
	v_mfma_f32_32x32x16_bf16 v[64:79], v[226:229], v[120:123], v[64:79]
	ds_read_b128 v[226:229], v220 offset:13056
	s_waitcnt lgkmcnt(3)
	v_mfma_f32_32x32x16_bf16 v[80:95], v[230:233], v[124:127], v[80:95]
	ds_read_b128 v[230:233], v220 offset:288
	s_waitcnt lgkmcnt(3)
	v_mfma_f32_32x32x16_bf16 v[64:79], v[234:237], v[124:127], v[64:79]
	ds_read_b128 v[234:237], v220 offset:13088
	s_waitcnt lgkmcnt(3)
	v_mfma_f32_32x32x16_bf16 v[80:95], v[222:225], v[128:131], v[80:95]
	ds_read_b128 v[222:225], v220 offset:320
	s_waitcnt lgkmcnt(3)
	v_mfma_f32_32x32x16_bf16 v[64:79], v[226:229], v[128:131], v[64:79]
	ds_read_b128 v[226:229], v220 offset:13120
	s_waitcnt lgkmcnt(3)
	v_mfma_f32_32x32x16_bf16 v[80:95], v[230:233], v[132:135], v[80:95]
	ds_read_b128 v[230:233], v220 offset:352
	s_waitcnt lgkmcnt(3)
	v_mfma_f32_32x32x16_bf16 v[64:79], v[234:237], v[132:135], v[64:79]
	ds_read_b128 v[234:237], v220 offset:13152
	s_waitcnt lgkmcnt(3)
	v_mfma_f32_32x32x16_bf16 v[80:95], v[222:225], v[136:139], v[80:95]
	s_waitcnt lgkmcnt(2)
	v_mfma_f32_32x32x16_bf16 v[64:79], v[226:229], v[136:139], v[64:79]
	s_waitcnt lgkmcnt(1)
	v_mfma_f32_32x32x16_bf16 v[80:95], v[230:233], v[140:143], v[80:95]
	s_waitcnt lgkmcnt(0)
	v_mfma_f32_32x32x16_bf16 v[64:79], v[234:237], v[140:143], v[64:79]
	s_setprio 0
	s_nop 0
	s_mov_b64 vcc, s[30:31]
	s_cbranch_vccnz .Lattn_hw2_v5
	s_waitcnt vmcnt(0)
	s_branch .Lattn_hw2_go

; #define ATT_LOAD(kr, vr, t) do { const bf16_t* kp_ = KVb + (size_t)(t) * 64 * 2048 + kn_off; \
;         kr[0] = *(const u32x4*)kp_; kr[1] = *(const u32x4*)(kp_ + 32 * 2048); kr[2] = *(const u32x4*)(KPEb + (t) * 64 * 64 + kp_off); \
;         const bf16_t* vp_ = VTb + (t) * 64 + v_off; vr[0] = *(const u32x4*)vp_; vr[1] = *(const u32x4*)(vp_ + 64 * SEQ); } while (0)
; #define ATT_TILE(t, slot) do { const int rel_ = (t) - 4 * qb; if (rel_ <= (w >> 1)) { qk_softmax((t), (slot), rel_ == (w >> 1)); pv(slot); } } while (0)
; DI void attn_unit(const Params& P, LAS unsigned char* lds, int b, int h, int qb, bool dry) {
;     ...
;     ATT_LOAD(kA, vA, 0);
;     __syncthreads();
;     ATT_STORE(kA, vA, 0);
;     ATT_LOAD(kA, vA, 1);
;     __syncthreads();
;     for (int kt = 0; kt < nt; kt += 2) {
;         const bool more2 = kt + 2 < nt;
;         if (more2) ATT_LOAD(kB, vB, kt + 2);
;         ATT_TILE(kt, 0);
;         ATT_STORE(kA, vA, 1);
;         __syncthreads();
;         if (more2) ATT_LOAD(kA, vA, kt + 3);
;         ATT_TILE(kt + 1, 1);
.Lattn_wdone2:
	s_not_b64 s[40:41], s[30:31]
	s_waitcnt lgkmcnt(0)
	s_mov_b64 vcc, s[30:31]
	s_cbranch_vccz .Lattn_pfA2_skip
	v_add_co_u32_e32 v64, vcc, 0xfffe0000, v192
	s_nop 1
	v_addc_co_u32_e32 v65, vcc, -1, v193, vcc
	global_load_dwordx4 v[144:147], v[64:65], off
	global_load_dwordx4 v[148:151], v[192:193], off
	global_load_dwordx4 v[152:155], v[188:189], off
	v_add_co_u32_e32 v64, vcc, 0xffe00000, v190
	s_nop 1
	v_addc_co_u32_e32 v65, vcc, -1, v191, vcc
	global_load_dwordx4 v[156:159], v[64:65], off
	global_load_dwordx4 v[160:163], v[190:191], off
.Lattn_pfA2_skip:
	s_andn2_b64 vcc, exec, s[30:31]
	s_barrier
	s_cbranch_vccnz .LBB0_64
	s_add_i32 s37, s37, -1
	s_cmp_gt_i32 s37, s36
	s_cbranch_scc0 .LBB0_65
